# combined edits plus no s_setprio toggling in the K-loops
# baseline (speedup 1.0000x reference)
.Lp1b_body:
	s_add_i32 s12, s75, 2
	s_add_u32 s30, s28, 0xfff00080
	s_addc_u32 s31, s29, -1
	s_cmp_eq_u32 s72, s75
	s_cselect_b32 s35, s68, s31
	s_cselect_b32 s34, s69, s30
	s_cselect_b32 s31, s70, s74
	s_cselect_b32 s30, s71, s73
	ds_read_b128 v[168:171], v160
	ds_read_b128 v[176:179], v160 offset:1024
	ds_read_b128 v[180:183], v160 offset:2048
	ds_read_b128 v[184:187], v160 offset:3072
	ds_read_b128 v[188:191], v160 offset:16384
	ds_read_b128 v[192:195], v160 offset:17408
	ds_read_b128 v[196:199], v160 offset:18432
	ds_read_b128 v[200:203], v160 offset:19456
	s_add_i32 m0, s49, 0xc000
	ds_read_b128 v[204:207], v163
	ds_read_b128 v[208:211], v163 offset:1024
	ds_read_b128 v[212:215], v163 offset:2048
	ds_read_b128 v[216:219], v163 offset:3072
	ds_read_b128 v[220:223], v163 offset:4096
	ds_read_b128 v[224:227], v163 offset:5120
	ds_read_b128 v[228:231], v163 offset:6144
	global_load_lds_dwordx4 v146, s[28:29]
	s_add_i32 m0, s49, 0xe000
	ds_read_b128 v[236:239], v163 offset:7168
	global_load_lds_dwordx4 v148, s[28:29]
	s_waitcnt vmcnt(8) lgkmcnt(0)
	s_barrier
	v_mfma_f32_16x16x32_bf16 v[132:135], v[168:171], v[204:207], v[132:135]
	v_mfma_f32_16x16x32_bf16 v[128:131], v[180:183], v[204:207], v[128:131]
	v_mfma_f32_16x16x32_bf16 v[116:119], v[168:171], v[212:215], v[116:119]
	v_mfma_f32_16x16x32_bf16 v[112:115], v[180:183], v[212:215], v[112:115]
	v_mfma_f32_16x16x32_bf16 v[100:103], v[168:171], v[220:223], v[100:103]
	v_mfma_f32_16x16x32_bf16 v[96:99], v[180:183], v[220:223], v[96:99]
	v_mfma_f32_16x16x32_bf16 v[84:87], v[168:171], v[228:231], v[84:87]
	v_mfma_f32_16x16x32_bf16 v[80:83], v[180:183], v[228:231], v[80:83]
	v_mfma_f32_16x16x32_bf16 v[132:135], v[176:179], v[208:211], v[132:135]
	v_mfma_f32_16x16x32_bf16 v[128:131], v[184:187], v[208:211], v[128:131]
	v_mfma_f32_16x16x32_bf16 v[116:119], v[176:179], v[216:219], v[116:119]
	v_mfma_f32_16x16x32_bf16 v[112:115], v[184:187], v[216:219], v[112:115]
	v_mfma_f32_16x16x32_bf16 v[100:103], v[176:179], v[224:227], v[100:103]
	v_mfma_f32_16x16x32_bf16 v[96:99], v[184:187], v[224:227], v[96:99]
	v_mfma_f32_16x16x32_bf16 v[84:87], v[176:179], v[236:239], v[84:87]
	v_mfma_f32_16x16x32_bf16 v[80:83], v[184:187], v[236:239], v[80:83]
	v_mfma_f32_16x16x32_bf16 v[124:127], v[188:191], v[204:207], v[124:127]
	v_mfma_f32_16x16x32_bf16 v[120:123], v[196:199], v[204:207], v[120:123]
	v_mfma_f32_16x16x32_bf16 v[108:111], v[188:191], v[212:215], v[108:111]
	v_mfma_f32_16x16x32_bf16 v[104:107], v[196:199], v[212:215], v[104:107]
	v_mfma_f32_16x16x32_bf16 v[92:95], v[188:191], v[220:223], v[92:95]
	v_mfma_f32_16x16x32_bf16 v[88:91], v[196:199], v[220:223], v[88:91]
	v_mfma_f32_16x16x32_bf16 v[76:79], v[188:191], v[228:231], v[76:79]
	v_mfma_f32_16x16x32_bf16 v[72:75], v[196:199], v[228:231], v[72:75]
	v_mfma_f32_16x16x32_bf16 v[124:127], v[192:195], v[208:211], v[124:127]
	v_mfma_f32_16x16x32_bf16 v[120:123], v[200:203], v[208:211], v[120:123]
	v_mfma_f32_16x16x32_bf16 v[108:111], v[192:195], v[216:219], v[108:111]
	v_mfma_f32_16x16x32_bf16 v[104:107], v[200:203], v[216:219], v[104:107]
	v_mfma_f32_16x16x32_bf16 v[92:95], v[192:195], v[224:227], v[92:95]
	v_mfma_f32_16x16x32_bf16 v[88:91], v[200:203], v[224:227], v[88:91]
	v_mfma_f32_16x16x32_bf16 v[76:79], v[192:195], v[236:239], v[76:79]
	v_mfma_f32_16x16x32_bf16 v[72:75], v[200:203], v[236:239], v[72:75]
	s_barrier
	s_add_i32 s36, s59, s48
	s_mov_b32 m0, s36
	ds_read_b128 v[204:207], v163 offset:16384
	ds_read_b128 v[208:211], v163 offset:17408
	ds_read_b128 v[212:215], v163 offset:18432
	ds_read_b128 v[216:219], v163 offset:19456
	global_load_lds_dwordx4 v138, s[30:31]
	s_add_i32 m0, s36, 0x2000
	s_add_u32 s36, s30, 0x100000
	s_addc_u32 s37, s31, 0
	s_add_i32 s75, s60, s48
	global_load_lds_dwordx4 v142, s[30:31]
	s_mov_b32 m0, s75
	ds_read_b128 v[236:239], v163 offset:23552
	global_load_lds_dwordx4 v138, s[36:37]
	s_add_i32 m0, s75, 0x2000
	ds_read_b128 v[228:231], v163 offset:22528
	global_load_lds_dwordx4 v142, s[36:37]
	s_mov_b32 m0, s49
	ds_read_b128 v[224:227], v163 offset:21504
	global_load_lds_dwordx4 v136, s[34:35]
	s_mov_b32 m0, s50
	ds_read_b128 v[220:223], v163 offset:20480
	global_load_lds_dwordx4 v140, s[34:35]
	s_waitcnt vmcnt(8) lgkmcnt(0)
	s_barrier
	v_mfma_f32_16x16x32_bf16 v[68:71], v[168:171], v[204:207], v[68:71]
	v_mfma_f32_16x16x32_bf16 v[64:67], v[180:183], v[204:207], v[64:67]
	v_mfma_f32_16x16x32_bf16 v[52:55], v[168:171], v[212:215], v[52:55]
	v_mfma_f32_16x16x32_bf16 v[48:51], v[180:183], v[212:215], v[48:51]
	v_mfma_f32_16x16x32_bf16 v[36:39], v[168:171], v[220:223], v[36:39]
	v_mfma_f32_16x16x32_bf16 v[32:35], v[180:183], v[220:223], v[32:35]
	v_mfma_f32_16x16x32_bf16 v[20:23], v[168:171], v[228:231], v[20:23]
	v_mfma_f32_16x16x32_bf16 v[16:19], v[180:183], v[228:231], v[16:19]
	v_mfma_f32_16x16x32_bf16 v[68:71], v[176:179], v[208:211], v[68:71]
	v_mfma_f32_16x16x32_bf16 v[64:67], v[184:187], v[208:211], v[64:67]
	v_mfma_f32_16x16x32_bf16 v[52:55], v[176:179], v[216:219], v[52:55]
	v_mfma_f32_16x16x32_bf16 v[48:51], v[184:187], v[216:219], v[48:51]
	v_mfma_f32_16x16x32_bf16 v[36:39], v[176:179], v[224:227], v[36:39]
	v_mfma_f32_16x16x32_bf16 v[32:35], v[184:187], v[224:227], v[32:35]
	v_mfma_f32_16x16x32_bf16 v[20:23], v[176:179], v[236:239], v[20:23]
	v_mfma_f32_16x16x32_bf16 v[16:19], v[184:187], v[236:239], v[16:19]
	v_mfma_f32_16x16x32_bf16 v[60:63], v[188:191], v[204:207], v[60:63]
	v_mfma_f32_16x16x32_bf16 v[56:59], v[196:199], v[204:207], v[56:59]
	v_mfma_f32_16x16x32_bf16 v[44:47], v[188:191], v[212:215], v[44:47]
	v_mfma_f32_16x16x32_bf16 v[40:43], v[196:199], v[212:215], v[40:43]
	v_mfma_f32_16x16x32_bf16 v[28:31], v[188:191], v[220:223], v[28:31]
	v_mfma_f32_16x16x32_bf16 v[24:27], v[196:199], v[220:223], v[24:27]
	v_mfma_f32_16x16x32_bf16 v[12:15], v[188:191], v[228:231], v[12:15]
	v_mfma_f32_16x16x32_bf16 v[6:9], v[196:199], v[228:231], v[8:11]
	v_mfma_f32_16x16x32_bf16 v[60:63], v[192:195], v[208:211], v[60:63]
	v_mfma_f32_16x16x32_bf16 v[56:59], v[200:203], v[208:211], v[56:59]
	v_mfma_f32_16x16x32_bf16 v[44:47], v[192:195], v[216:219], v[44:47]
	v_mfma_f32_16x16x32_bf16 v[40:43], v[200:203], v[216:219], v[40:43]
	v_mfma_f32_16x16x32_bf16 v[28:31], v[192:195], v[224:227], v[28:31]
	v_mfma_f32_16x16x32_bf16 v[24:27], v[200:203], v[224:227], v[24:27]
	v_mfma_f32_16x16x32_bf16 v[12:15], v[192:195], v[236:239], v[12:15]
	v_mfma_f32_16x16x32_bf16 v[6:9], v[200:203], v[236:239], v[6:9]
	s_barrier
	s_add_i32 s36, 0, 0x18000
	s_add_i32 s37, 0, 0x1c000
	ds_read_b128 v[168:171], v160 offset:32768
	ds_read_b128 v[176:179], v160 offset:33792
	ds_read_b128 v[180:183], v160 offset:34816
	ds_read_b128 v[184:187], v160 offset:35840
	ds_read_b128 v[188:191], v160 offset:49152
	ds_read_b128 v[192:195], v160 offset:50176
	ds_read_b128 v[196:199], v160 offset:51200
	ds_read_b128 v[200:203], v160 offset:52224
	s_add_u32 s34, s34, 0x100000
	s_addc_u32 s35, s35, 0
	s_mov_b32 m0, s51
	ds_read_b128 v[204:207], v163 offset:32768
	ds_read_b128 v[208:211], v163 offset:33792
	ds_read_b128 v[212:215], v163 offset:34816
	ds_read_b128 v[216:219], v163 offset:35840
	ds_read_b128 v[220:223], v163 offset:36864
	ds_read_b128 v[224:227], v163 offset:37888
	ds_read_b128 v[228:231], v163 offset:38912
	global_load_lds_dwordx4 v136, s[34:35]
	s_mov_b32 m0, s52
	ds_read_b128 v[236:239], v163 offset:39936
	global_load_lds_dwordx4 v140, s[34:35]
	s_waitcnt vmcnt(8) lgkmcnt(0)
	s_barrier
	v_mfma_f32_16x16x32_bf16 v[132:135], v[168:171], v[204:207], v[132:135]
	v_mfma_f32_16x16x32_bf16 v[128:131], v[180:183], v[204:207], v[128:131]
	v_mfma_f32_16x16x32_bf16 v[116:119], v[168:171], v[212:215], v[116:119]
	v_mfma_f32_16x16x32_bf16 v[112:115], v[180:183], v[212:215], v[112:115]
	v_mfma_f32_16x16x32_bf16 v[100:103], v[168:171], v[220:223], v[100:103]
	v_mfma_f32_16x16x32_bf16 v[96:99], v[180:183], v[220:223], v[96:99]
	v_mfma_f32_16x16x32_bf16 v[84:87], v[168:171], v[228:231], v[84:87]
	v_mfma_f32_16x16x32_bf16 v[80:83], v[180:183], v[228:231], v[80:83]
	v_mfma_f32_16x16x32_bf16 v[132:135], v[176:179], v[208:211], v[132:135]
	v_mfma_f32_16x16x32_bf16 v[128:131], v[184:187], v[208:211], v[128:131]
	v_mfma_f32_16x16x32_bf16 v[116:119], v[176:179], v[216:219], v[116:119]
	v_mfma_f32_16x16x32_bf16 v[112:115], v[184:187], v[216:219], v[112:115]
	v_mfma_f32_16x16x32_bf16 v[100:103], v[176:179], v[224:227], v[100:103]
	v_mfma_f32_16x16x32_bf16 v[96:99], v[184:187], v[224:227], v[96:99]
	v_mfma_f32_16x16x32_bf16 v[84:87], v[176:179], v[236:239], v[84:87]
	v_mfma_f32_16x16x32_bf16 v[80:83], v[184:187], v[236:239], v[80:83]
	v_mfma_f32_16x16x32_bf16 v[124:127], v[188:191], v[204:207], v[124:127]
	v_mfma_f32_16x16x32_bf16 v[120:123], v[196:199], v[204:207], v[120:123]
	v_mfma_f32_16x16x32_bf16 v[108:111], v[188:191], v[212:215], v[108:111]
	v_mfma_f32_16x16x32_bf16 v[104:107], v[196:199], v[212:215], v[104:107]
	v_mfma_f32_16x16x32_bf16 v[92:95], v[188:191], v[220:223], v[92:95]
	v_mfma_f32_16x16x32_bf16 v[88:91], v[196:199], v[220:223], v[88:91]
	v_mfma_f32_16x16x32_bf16 v[76:79], v[188:191], v[228:231], v[76:79]
	v_mfma_f32_16x16x32_bf16 v[72:75], v[196:199], v[228:231], v[72:75]
	v_mfma_f32_16x16x32_bf16 v[124:127], v[192:195], v[208:211], v[124:127]
	v_mfma_f32_16x16x32_bf16 v[120:123], v[200:203], v[208:211], v[120:123]
	v_mfma_f32_16x16x32_bf16 v[108:111], v[192:195], v[216:219], v[108:111]
	v_mfma_f32_16x16x32_bf16 v[104:107], v[200:203], v[216:219], v[104:107]
	v_mfma_f32_16x16x32_bf16 v[92:95], v[192:195], v[224:227], v[92:95]
	v_mfma_f32_16x16x32_bf16 v[88:91], v[200:203], v[224:227], v[88:91]
	v_mfma_f32_16x16x32_bf16 v[76:79], v[192:195], v[236:239], v[76:79]
	v_mfma_f32_16x16x32_bf16 v[72:75], v[200:203], v[236:239], v[72:75]
	s_barrier
	s_add_u32 s98, s30, s10
	s_addc_u32 s99, s31, s11
	s_add_u32 s100, s34, s10
	s_addc_u32 s101, s35, s11
	s_sub_u32 s100, s100, 0x100000
	s_subb_u32 s101, s101, 0
	s_add_i32 s34, s36, s48
	s_mov_b32 m0, s34
	ds_read_b128 v[152:155], v163 offset:49152
	ds_read_b128 v[164:167], v163 offset:50176
	ds_read_b128 v[204:207], v163 offset:51200
	ds_read_b128 v[208:211], v163 offset:52224
	global_load_lds_dwordx4 v138, s[98:99]
	s_add_i32 m0, s34, 0x2000
	s_add_u32 s30, s30, 0x100080
	s_addc_u32 s31, s31, 0
	s_add_i32 s34, s37, s48
	global_load_lds_dwordx4 v142, s[98:99]
	s_mov_b32 m0, s34
	ds_read_b128 v[224:227], v163 offset:56320
	global_load_lds_dwordx4 v138, s[30:31]
	s_add_i32 m0, s34, 0x2000
	ds_read_b128 v[220:223], v163 offset:55296
	global_load_lds_dwordx4 v142, s[30:31]
	s_mov_b32 m0, s56
	ds_read_b128 v[216:219], v163 offset:54272
	global_load_lds_dwordx4 v136, s[100:101]
	s_mov_b32 m0, s57
	ds_read_b128 v[212:215], v163 offset:53248
	global_load_lds_dwordx4 v140, s[100:101]
	s_waitcnt vmcnt(8) lgkmcnt(0)
	s_barrier
	v_mfma_f32_16x16x32_bf16 v[68:71], v[168:171], v[152:155], v[68:71]
	v_mfma_f32_16x16x32_bf16 v[64:67], v[180:183], v[152:155], v[64:67]
	v_mfma_f32_16x16x32_bf16 v[52:55], v[168:171], v[204:207], v[52:55]
	v_mfma_f32_16x16x32_bf16 v[48:51], v[180:183], v[204:207], v[48:51]
	v_mfma_f32_16x16x32_bf16 v[36:39], v[168:171], v[212:215], v[36:39]
	v_mfma_f32_16x16x32_bf16 v[32:35], v[180:183], v[212:215], v[32:35]
	v_mfma_f32_16x16x32_bf16 v[20:23], v[168:171], v[220:223], v[20:23]
	v_mfma_f32_16x16x32_bf16 v[16:19], v[180:183], v[220:223], v[16:19]
	v_mfma_f32_16x16x32_bf16 v[68:71], v[176:179], v[164:167], v[68:71]
	v_mfma_f32_16x16x32_bf16 v[64:67], v[184:187], v[164:167], v[64:67]
	v_mfma_f32_16x16x32_bf16 v[52:55], v[176:179], v[208:211], v[52:55]
	v_mfma_f32_16x16x32_bf16 v[48:51], v[184:187], v[208:211], v[48:51]
	v_mfma_f32_16x16x32_bf16 v[36:39], v[176:179], v[216:219], v[36:39]
	v_mfma_f32_16x16x32_bf16 v[32:35], v[184:187], v[216:219], v[32:35]
	v_mfma_f32_16x16x32_bf16 v[20:23], v[176:179], v[224:227], v[20:23]
	v_mfma_f32_16x16x32_bf16 v[16:19], v[184:187], v[224:227], v[16:19]
	v_mfma_f32_16x16x32_bf16 v[60:63], v[188:191], v[152:155], v[60:63]
	v_mfma_f32_16x16x32_bf16 v[56:59], v[196:199], v[152:155], v[56:59]
	v_mfma_f32_16x16x32_bf16 v[44:47], v[188:191], v[204:207], v[44:47]
	v_mfma_f32_16x16x32_bf16 v[40:43], v[196:199], v[204:207], v[40:43]
	v_mfma_f32_16x16x32_bf16 v[28:31], v[188:191], v[212:215], v[28:31]
	v_mfma_f32_16x16x32_bf16 v[24:27], v[196:199], v[212:215], v[24:27]
	v_mfma_f32_16x16x32_bf16 v[10:13], v[188:191], v[220:223], v[12:15]
	v_mfma_f32_16x16x32_bf16 v[6:9], v[196:199], v[220:223], v[6:9]
	v_mfma_f32_16x16x32_bf16 v[60:63], v[192:195], v[164:167], v[60:63]
	v_mfma_f32_16x16x32_bf16 v[56:59], v[200:203], v[164:167], v[56:59]
	v_mfma_f32_16x16x32_bf16 v[44:47], v[192:195], v[208:211], v[44:47]
	v_mfma_f32_16x16x32_bf16 v[40:43], v[200:203], v[208:211], v[40:43]
	v_mfma_f32_16x16x32_bf16 v[28:31], v[192:195], v[216:219], v[28:31]
	v_mfma_f32_16x16x32_bf16 v[24:27], v[200:203], v[216:219], v[24:27]
	v_mfma_f32_16x16x32_bf16 v[12:15], v[192:195], v[224:227], v[10:13]
	v_mfma_f32_16x16x32_bf16 v[8:11], v[200:203], v[224:227], v[6:9]
	s_barrier
	s_add_u32 s28, s28, 0x100
	s_addc_u32 s29, s29, 0
	s_add_u32 s73, s73, 0x100
	s_addc_u32 s74, s74, 0
	s_cmp_ge_i32 s12, s67
	s_cbranch_scc0 .Lp1b_top
	s_branch .Lp1b_epi

.LBB0_236:
	s_add_i32 s12, s75, 2
	s_add_u32 s30, s28, 0xfff00080
	s_addc_u32 s31, s29, -1
	s_cmp_eq_u32 s72, s75
	s_cselect_b32 s35, s68, s31
	s_cselect_b32 s34, s69, s30
	s_cselect_b32 s31, s70, s74
	s_cselect_b32 s30, s71, s73
	s_cmpk_lt_i32 s3, 0x56
	s_mov_b32 s78, 0xac00
	s_cselect_b32 s75, s78, 0x4000
	s_mul_i32 s36, s75, s33
	s_add_u32 s36, s38, s36
	s_addc_u32 s37, s39, 0
	global_load_dwordx4 v[152:155], v173, s[36:37] nt
	s_add_u32 s76, s36, s75
	s_addc_u32 s77, s37, 0
	global_load_dwordx4 v[164:167], v173, s[76:77] nt
	s_add_i32 s33, s33, 2
	v_add_u32_e32 v174, -2, v174
	ds_read_b128 v[168:171], v160
	ds_read_b128 v[176:179], v160 offset:1024
	ds_read_b128 v[180:183], v160 offset:2048
	ds_read_b128 v[184:187], v160 offset:3072
	ds_read_b128 v[188:191], v160 offset:16384
	ds_read_b128 v[192:195], v160 offset:17408
	ds_read_b128 v[196:199], v160 offset:18432
	ds_read_b128 v[200:203], v160 offset:19456
	s_add_i32 m0, s49, 0xc000
	ds_read_b128 v[204:207], v163
	ds_read_b128 v[208:211], v163 offset:1024
	ds_read_b128 v[212:215], v163 offset:2048
	ds_read_b128 v[216:219], v163 offset:3072
	ds_read_b128 v[220:223], v163 offset:4096
	ds_read_b128 v[224:227], v163 offset:5120
	ds_read_b128 v[228:231], v163 offset:6144
	global_load_lds_dwordx4 v146, s[28:29]
	s_add_i32 m0, s49, 0xe000
	ds_read_b128 v[236:239], v163 offset:7168
	global_load_lds_dwordx4 v148, s[28:29]
	s_waitcnt vmcnt(10) lgkmcnt(0)
	s_barrier
	v_mfma_f32_16x16x32_bf16 v[132:135], v[168:171], v[204:207], v[132:135]
	v_mfma_f32_16x16x32_bf16 v[128:131], v[180:183], v[204:207], v[128:131]
	v_mfma_f32_16x16x32_bf16 v[116:119], v[168:171], v[212:215], v[116:119]
	v_mfma_f32_16x16x32_bf16 v[112:115], v[180:183], v[212:215], v[112:115]
	v_mfma_f32_16x16x32_bf16 v[100:103], v[168:171], v[220:223], v[100:103]
	v_mfma_f32_16x16x32_bf16 v[96:99], v[180:183], v[220:223], v[96:99]
	v_mfma_f32_16x16x32_bf16 v[84:87], v[168:171], v[228:231], v[84:87]
	v_mfma_f32_16x16x32_bf16 v[80:83], v[180:183], v[228:231], v[80:83]
	v_mfma_f32_16x16x32_bf16 v[132:135], v[176:179], v[208:211], v[132:135]
	v_mfma_f32_16x16x32_bf16 v[128:131], v[184:187], v[208:211], v[128:131]
	v_mfma_f32_16x16x32_bf16 v[116:119], v[176:179], v[216:219], v[116:119]
	v_mfma_f32_16x16x32_bf16 v[112:115], v[184:187], v[216:219], v[112:115]
	v_mfma_f32_16x16x32_bf16 v[100:103], v[176:179], v[224:227], v[100:103]
	v_mfma_f32_16x16x32_bf16 v[96:99], v[184:187], v[224:227], v[96:99]
	v_mfma_f32_16x16x32_bf16 v[84:87], v[176:179], v[236:239], v[84:87]
	v_mfma_f32_16x16x32_bf16 v[80:83], v[184:187], v[236:239], v[80:83]
	v_mfma_f32_16x16x32_bf16 v[124:127], v[188:191], v[204:207], v[124:127]
	v_mfma_f32_16x16x32_bf16 v[120:123], v[196:199], v[204:207], v[120:123]
	v_mfma_f32_16x16x32_bf16 v[108:111], v[188:191], v[212:215], v[108:111]
	v_mfma_f32_16x16x32_bf16 v[104:107], v[196:199], v[212:215], v[104:107]
	v_mfma_f32_16x16x32_bf16 v[92:95], v[188:191], v[220:223], v[92:95]
	v_mfma_f32_16x16x32_bf16 v[88:91], v[196:199], v[220:223], v[88:91]
	v_mfma_f32_16x16x32_bf16 v[76:79], v[188:191], v[228:231], v[76:79]
	v_mfma_f32_16x16x32_bf16 v[72:75], v[196:199], v[228:231], v[72:75]
	v_mfma_f32_16x16x32_bf16 v[124:127], v[192:195], v[208:211], v[124:127]
	v_mfma_f32_16x16x32_bf16 v[120:123], v[200:203], v[208:211], v[120:123]
	v_mfma_f32_16x16x32_bf16 v[108:111], v[192:195], v[216:219], v[108:111]
	v_mfma_f32_16x16x32_bf16 v[104:107], v[200:203], v[216:219], v[104:107]
	v_mfma_f32_16x16x32_bf16 v[92:95], v[192:195], v[224:227], v[92:95]
	v_mfma_f32_16x16x32_bf16 v[88:91], v[200:203], v[224:227], v[88:91]
	v_mfma_f32_16x16x32_bf16 v[76:79], v[192:195], v[236:239], v[76:79]
	v_mfma_f32_16x16x32_bf16 v[72:75], v[200:203], v[236:239], v[72:75]
	s_barrier
	s_add_i32 s36, s59, s48
	s_mov_b32 m0, s36
	ds_read_b128 v[204:207], v163 offset:16384
	ds_read_b128 v[208:211], v163 offset:17408
	ds_read_b128 v[212:215], v163 offset:18432
	ds_read_b128 v[216:219], v163 offset:19456
	global_load_lds_dwordx4 v138, s[30:31]
	s_add_i32 m0, s36, 0x2000
	s_add_u32 s36, s30, 0x100000
	s_addc_u32 s37, s31, 0
	s_add_i32 s75, s60, s48
	global_load_lds_dwordx4 v142, s[30:31]
	s_mov_b32 m0, s75
	ds_read_b128 v[236:239], v163 offset:23552
	global_load_lds_dwordx4 v138, s[36:37]
	s_add_i32 m0, s75, 0x2000
	ds_read_b128 v[228:231], v163 offset:22528
	global_load_lds_dwordx4 v142, s[36:37]
	s_mov_b32 m0, s49
	ds_read_b128 v[224:227], v163 offset:21504
	global_load_lds_dwordx4 v136, s[34:35]
	s_mov_b32 m0, s50
	ds_read_b128 v[220:223], v163 offset:20480
	global_load_lds_dwordx4 v140, s[34:35]
	s_waitcnt vmcnt(10) lgkmcnt(0)
	s_barrier
	v_mfma_f32_16x16x32_bf16 v[68:71], v[168:171], v[204:207], v[68:71]
	v_mfma_f32_16x16x32_bf16 v[64:67], v[180:183], v[204:207], v[64:67]
	v_mfma_f32_16x16x32_bf16 v[52:55], v[168:171], v[212:215], v[52:55]
	v_mfma_f32_16x16x32_bf16 v[48:51], v[180:183], v[212:215], v[48:51]
	v_mfma_f32_16x16x32_bf16 v[36:39], v[168:171], v[220:223], v[36:39]
	v_mfma_f32_16x16x32_bf16 v[32:35], v[180:183], v[220:223], v[32:35]
	v_mfma_f32_16x16x32_bf16 v[20:23], v[168:171], v[228:231], v[20:23]
	v_mfma_f32_16x16x32_bf16 v[16:19], v[180:183], v[228:231], v[16:19]
	v_mfma_f32_16x16x32_bf16 v[68:71], v[176:179], v[208:211], v[68:71]
	v_mfma_f32_16x16x32_bf16 v[64:67], v[184:187], v[208:211], v[64:67]
	v_mfma_f32_16x16x32_bf16 v[52:55], v[176:179], v[216:219], v[52:55]
	v_mfma_f32_16x16x32_bf16 v[48:51], v[184:187], v[216:219], v[48:51]
	v_mfma_f32_16x16x32_bf16 v[36:39], v[176:179], v[224:227], v[36:39]
	v_mfma_f32_16x16x32_bf16 v[32:35], v[184:187], v[224:227], v[32:35]
	v_mfma_f32_16x16x32_bf16 v[20:23], v[176:179], v[236:239], v[20:23]
	v_mfma_f32_16x16x32_bf16 v[16:19], v[184:187], v[236:239], v[16:19]
	v_mfma_f32_16x16x32_bf16 v[60:63], v[188:191], v[204:207], v[60:63]
	v_mfma_f32_16x16x32_bf16 v[56:59], v[196:199], v[204:207], v[56:59]
	v_mfma_f32_16x16x32_bf16 v[44:47], v[188:191], v[212:215], v[44:47]
	v_mfma_f32_16x16x32_bf16 v[40:43], v[196:199], v[212:215], v[40:43]
	v_mfma_f32_16x16x32_bf16 v[28:31], v[188:191], v[220:223], v[28:31]
	v_mfma_f32_16x16x32_bf16 v[24:27], v[196:199], v[220:223], v[24:27]
	v_mfma_f32_16x16x32_bf16 v[12:15], v[188:191], v[228:231], v[12:15]
	v_mfma_f32_16x16x32_bf16 v[6:9], v[196:199], v[228:231], v[8:11]
	v_mfma_f32_16x16x32_bf16 v[60:63], v[192:195], v[208:211], v[60:63]
	v_mfma_f32_16x16x32_bf16 v[56:59], v[200:203], v[208:211], v[56:59]
	v_mfma_f32_16x16x32_bf16 v[44:47], v[192:195], v[216:219], v[44:47]
	v_mfma_f32_16x16x32_bf16 v[40:43], v[200:203], v[216:219], v[40:43]
	v_mfma_f32_16x16x32_bf16 v[28:31], v[192:195], v[224:227], v[28:31]
	v_mfma_f32_16x16x32_bf16 v[24:27], v[200:203], v[224:227], v[24:27]
	v_mfma_f32_16x16x32_bf16 v[12:15], v[192:195], v[236:239], v[12:15]
	v_mfma_f32_16x16x32_bf16 v[6:9], v[200:203], v[236:239], v[6:9]
	s_barrier
	s_add_i32 s36, 0, 0x18000
	s_add_i32 s37, 0, 0x1c000
	ds_read_b128 v[168:171], v160 offset:32768
	ds_read_b128 v[176:179], v160 offset:33792
	ds_read_b128 v[180:183], v160 offset:34816
	ds_read_b128 v[184:187], v160 offset:35840
	ds_read_b128 v[188:191], v160 offset:49152
	ds_read_b128 v[192:195], v160 offset:50176
	ds_read_b128 v[196:199], v160 offset:51200
	ds_read_b128 v[200:203], v160 offset:52224
	s_add_u32 s34, s34, 0x100000
	s_addc_u32 s35, s35, 0
	s_mov_b32 m0, s51
	ds_read_b128 v[204:207], v163 offset:32768
	ds_read_b128 v[208:211], v163 offset:33792
	ds_read_b128 v[212:215], v163 offset:34816
	ds_read_b128 v[216:219], v163 offset:35840
	ds_read_b128 v[220:223], v163 offset:36864
	ds_read_b128 v[224:227], v163 offset:37888
	ds_read_b128 v[228:231], v163 offset:38912
	global_load_lds_dwordx4 v136, s[34:35]
	s_mov_b32 m0, s52
	ds_read_b128 v[236:239], v163 offset:39936
	global_load_lds_dwordx4 v140, s[34:35]
	s_waitcnt vmcnt(8) lgkmcnt(0)
	s_barrier
	v_mfma_f32_16x16x32_bf16 v[132:135], v[168:171], v[204:207], v[132:135]
	v_mfma_f32_16x16x32_bf16 v[128:131], v[180:183], v[204:207], v[128:131]
	v_mfma_f32_16x16x32_bf16 v[116:119], v[168:171], v[212:215], v[116:119]
	v_mfma_f32_16x16x32_bf16 v[112:115], v[180:183], v[212:215], v[112:115]
	v_mfma_f32_16x16x32_bf16 v[100:103], v[168:171], v[220:223], v[100:103]
	v_max3_f32 v0, v0, |v152|, |v164|
	v_mfma_f32_16x16x32_bf16 v[96:99], v[180:183], v[220:223], v[96:99]
	v_max3_f32 v1, v1, |v153|, |v165|
	v_mfma_f32_16x16x32_bf16 v[84:87], v[168:171], v[228:231], v[84:87]
	v_max3_f32 v2, v2, |v154|, |v166|
	v_mfma_f32_16x16x32_bf16 v[80:83], v[180:183], v[228:231], v[80:83]
	v_max3_f32 v3, v3, |v155|, |v167|
	v_mfma_f32_16x16x32_bf16 v[132:135], v[176:179], v[208:211], v[132:135]
	v_mfma_f32_16x16x32_bf16 v[128:131], v[184:187], v[208:211], v[128:131]
	v_mfma_f32_16x16x32_bf16 v[116:119], v[176:179], v[216:219], v[116:119]
	v_mfma_f32_16x16x32_bf16 v[112:115], v[184:187], v[216:219], v[112:115]
	v_mfma_f32_16x16x32_bf16 v[100:103], v[176:179], v[224:227], v[100:103]
	v_mfma_f32_16x16x32_bf16 v[96:99], v[184:187], v[224:227], v[96:99]
	v_mfma_f32_16x16x32_bf16 v[84:87], v[176:179], v[236:239], v[84:87]
	v_mfma_f32_16x16x32_bf16 v[80:83], v[184:187], v[236:239], v[80:83]
	v_mfma_f32_16x16x32_bf16 v[124:127], v[188:191], v[204:207], v[124:127]
	v_mfma_f32_16x16x32_bf16 v[120:123], v[196:199], v[204:207], v[120:123]
	v_mfma_f32_16x16x32_bf16 v[108:111], v[188:191], v[212:215], v[108:111]
	v_mfma_f32_16x16x32_bf16 v[104:107], v[196:199], v[212:215], v[104:107]
	v_mfma_f32_16x16x32_bf16 v[92:95], v[188:191], v[220:223], v[92:95]
	v_mfma_f32_16x16x32_bf16 v[88:91], v[196:199], v[220:223], v[88:91]
	v_mfma_f32_16x16x32_bf16 v[76:79], v[188:191], v[228:231], v[76:79]
	v_mfma_f32_16x16x32_bf16 v[72:75], v[196:199], v[228:231], v[72:75]
	v_mfma_f32_16x16x32_bf16 v[124:127], v[192:195], v[208:211], v[124:127]
	v_mfma_f32_16x16x32_bf16 v[120:123], v[200:203], v[208:211], v[120:123]
	v_mfma_f32_16x16x32_bf16 v[108:111], v[192:195], v[216:219], v[108:111]
	v_mfma_f32_16x16x32_bf16 v[104:107], v[200:203], v[216:219], v[104:107]
	v_mfma_f32_16x16x32_bf16 v[92:95], v[192:195], v[224:227], v[92:95]
	v_mfma_f32_16x16x32_bf16 v[88:91], v[200:203], v[224:227], v[88:91]
	v_mfma_f32_16x16x32_bf16 v[76:79], v[192:195], v[236:239], v[76:79]
	v_mfma_f32_16x16x32_bf16 v[72:75], v[200:203], v[236:239], v[72:75]
	s_barrier
	s_add_u32 s98, s30, s10
	s_addc_u32 s99, s31, s11
	s_add_u32 s100, s34, s10
	s_addc_u32 s101, s35, s11
	s_sub_u32 s100, s100, 0x100000
	s_subb_u32 s101, s101, 0
	s_add_i32 s34, s36, s48
	s_mov_b32 m0, s34
	ds_read_b128 v[152:155], v163 offset:49152
	ds_read_b128 v[164:167], v163 offset:50176
	ds_read_b128 v[204:207], v163 offset:51200
	ds_read_b128 v[208:211], v163 offset:52224
	global_load_lds_dwordx4 v138, s[98:99]
	s_add_i32 m0, s34, 0x2000
	s_add_u32 s30, s30, 0x100080
	s_addc_u32 s31, s31, 0
	s_add_i32 s34, s37, s48
	global_load_lds_dwordx4 v142, s[98:99]
	s_mov_b32 m0, s34
	ds_read_b128 v[224:227], v163 offset:56320
	global_load_lds_dwordx4 v138, s[30:31]
	s_add_i32 m0, s34, 0x2000
	ds_read_b128 v[220:223], v163 offset:55296
	global_load_lds_dwordx4 v142, s[30:31]
	s_mov_b32 m0, s56
	ds_read_b128 v[216:219], v163 offset:54272
	global_load_lds_dwordx4 v136, s[100:101]
	s_mov_b32 m0, s57
	ds_read_b128 v[212:215], v163 offset:53248
	global_load_lds_dwordx4 v140, s[100:101]
	s_waitcnt vmcnt(8) lgkmcnt(0)
	s_barrier
	v_mfma_f32_16x16x32_bf16 v[68:71], v[168:171], v[152:155], v[68:71]
	v_mfma_f32_16x16x32_bf16 v[64:67], v[180:183], v[152:155], v[64:67]
	v_mfma_f32_16x16x32_bf16 v[52:55], v[168:171], v[204:207], v[52:55]
	v_mfma_f32_16x16x32_bf16 v[48:51], v[180:183], v[204:207], v[48:51]
	v_mfma_f32_16x16x32_bf16 v[36:39], v[168:171], v[212:215], v[36:39]
	v_mfma_f32_16x16x32_bf16 v[32:35], v[180:183], v[212:215], v[32:35]
	v_mfma_f32_16x16x32_bf16 v[20:23], v[168:171], v[220:223], v[20:23]
	v_mfma_f32_16x16x32_bf16 v[16:19], v[180:183], v[220:223], v[16:19]
	v_mfma_f32_16x16x32_bf16 v[68:71], v[176:179], v[164:167], v[68:71]
	v_mfma_f32_16x16x32_bf16 v[64:67], v[184:187], v[164:167], v[64:67]
	v_mfma_f32_16x16x32_bf16 v[52:55], v[176:179], v[208:211], v[52:55]
	v_mfma_f32_16x16x32_bf16 v[48:51], v[184:187], v[208:211], v[48:51]
	v_mfma_f32_16x16x32_bf16 v[36:39], v[176:179], v[216:219], v[36:39]
	v_mfma_f32_16x16x32_bf16 v[32:35], v[184:187], v[216:219], v[32:35]
	v_mfma_f32_16x16x32_bf16 v[20:23], v[176:179], v[224:227], v[20:23]
	v_mfma_f32_16x16x32_bf16 v[16:19], v[184:187], v[224:227], v[16:19]
	v_mfma_f32_16x16x32_bf16 v[60:63], v[188:191], v[152:155], v[60:63]
	v_mfma_f32_16x16x32_bf16 v[56:59], v[196:199], v[152:155], v[56:59]
	v_mfma_f32_16x16x32_bf16 v[44:47], v[188:191], v[204:207], v[44:47]
	v_mfma_f32_16x16x32_bf16 v[40:43], v[196:199], v[204:207], v[40:43]
	v_mfma_f32_16x16x32_bf16 v[28:31], v[188:191], v[212:215], v[28:31]
	v_mfma_f32_16x16x32_bf16 v[24:27], v[196:199], v[212:215], v[24:27]
	v_mfma_f32_16x16x32_bf16 v[10:13], v[188:191], v[220:223], v[12:15]
	v_mfma_f32_16x16x32_bf16 v[6:9], v[196:199], v[220:223], v[6:9]
	v_mfma_f32_16x16x32_bf16 v[60:63], v[192:195], v[164:167], v[60:63]
	v_mfma_f32_16x16x32_bf16 v[56:59], v[200:203], v[164:167], v[56:59]
	v_mfma_f32_16x16x32_bf16 v[44:47], v[192:195], v[208:211], v[44:47]
	v_mfma_f32_16x16x32_bf16 v[40:43], v[200:203], v[208:211], v[40:43]
	v_mfma_f32_16x16x32_bf16 v[28:31], v[192:195], v[216:219], v[28:31]
	v_mfma_f32_16x16x32_bf16 v[24:27], v[200:203], v[216:219], v[24:27]
	v_mfma_f32_16x16x32_bf16 v[12:15], v[192:195], v[224:227], v[10:13]
	v_mfma_f32_16x16x32_bf16 v[8:11], v[200:203], v[224:227], v[6:9]
	s_barrier
	s_add_u32 s28, s28, 0x100
	s_addc_u32 s29, s29, 0
	s_add_u32 s73, s73, 0x100
	s_addc_u32 s74, s74, 0
	s_cmp_ge_i32 s12, s67
	s_cbranch_scc0 .LBB0_221

.LBB0_327:
	s_add_i32 s8, s74, 2
	s_add_u32 s34, s30, 0xfff80080
	s_addc_u32 s35, s31, -1
	s_cmp_eq_u32 s71, s74
	s_cselect_b32 s37, s67, s35
	s_cselect_b32 s36, s68, s34
	s_cselect_b32 s35, s69, s73
	s_cselect_b32 s34, s70, s72
	s_cmpk_lt_i32 s3, 0x56
	s_mov_b32 s79, 0xac00
	s_cselect_b32 s78, s79, 0x4000
	s_mul_i32 s74, s78, s33
	s_add_u32 s74, s38, s74
	s_addc_u32 s75, s39, 0
	global_load_dwordx4 v[152:155], v173, s[74:75] nt
	s_add_u32 s76, s74, s78
	s_addc_u32 s77, s75, 0
	global_load_dwordx4 v[156:159], v173, s[76:77] nt
	s_add_i32 s33, s33, 2
	v_add_u32_e32 v174, -2, v174
	ds_read_b128 v[160:163], v177
	ds_read_b128 v[164:167], v177 offset:1024
	ds_read_b128 v[168:171], v177 offset:2048
	ds_read_b128 v[182:185], v177 offset:3072
	ds_read_b128 v[186:189], v177 offset:16384
	ds_read_b128 v[190:193], v177 offset:17408
	ds_read_b128 v[194:197], v177 offset:18432
	ds_read_b128 v[198:201], v177 offset:19456
	s_add_i32 m0, s46, 0xc000
	ds_read_b128 v[202:205], v180
	ds_read_b128 v[206:209], v180 offset:1024
	ds_read_b128 v[210:213], v180 offset:2048
	ds_read_b128 v[214:217], v180 offset:3072
	ds_read_b128 v[218:221], v180 offset:4096
	ds_read_b128 v[222:225], v180 offset:5120
	ds_read_b128 v[226:229], v180 offset:6144
	global_load_lds_dwordx4 v146, s[30:31]
	s_add_i32 m0, s46, 0xe000
	ds_read_b128 v[230:233], v180 offset:7168
	global_load_lds_dwordx4 v148, s[30:31]
	s_waitcnt vmcnt(10) lgkmcnt(0)
	s_barrier
	v_mfma_i32_16x16x64_i8 v[132:135], v[160:163], v[202:205], v[132:135]
	v_mfma_i32_16x16x64_i8 v[128:131], v[168:171], v[202:205], v[128:131]
	v_mfma_i32_16x16x64_i8 v[124:127], v[160:163], v[210:213], v[124:127]
	v_mfma_i32_16x16x64_i8 v[120:123], v[168:171], v[210:213], v[120:123]
	v_mfma_i32_16x16x64_i8 v[112:115], v[160:163], v[218:221], v[112:115]
	v_mfma_i32_16x16x64_i8 v[104:107], v[168:171], v[218:221], v[104:107]
	v_mfma_i32_16x16x64_i8 v[96:99], v[160:163], v[226:229], v[96:99]
	v_mfma_i32_16x16x64_i8 v[88:91], v[168:171], v[226:229], v[88:91]
	v_mfma_i32_16x16x64_i8 v[132:135], v[164:167], v[206:209], v[132:135]
	v_mfma_i32_16x16x64_i8 v[128:131], v[182:185], v[206:209], v[128:131]
	v_mfma_i32_16x16x64_i8 v[124:127], v[164:167], v[214:217], v[124:127]
	v_mfma_i32_16x16x64_i8 v[120:123], v[182:185], v[214:217], v[120:123]
	v_mfma_i32_16x16x64_i8 v[112:115], v[164:167], v[222:225], v[112:115]
	v_mfma_i32_16x16x64_i8 v[104:107], v[182:185], v[222:225], v[104:107]
	v_mfma_i32_16x16x64_i8 v[96:99], v[164:167], v[230:233], v[96:99]
	v_mfma_i32_16x16x64_i8 v[88:91], v[182:185], v[230:233], v[88:91]
	v_mfma_i32_16x16x64_i8 v[116:119], v[186:189], v[202:205], v[116:119]
	v_mfma_i32_16x16x64_i8 v[108:111], v[194:197], v[202:205], v[108:111]
	v_mfma_i32_16x16x64_i8 v[100:103], v[186:189], v[210:213], v[100:103]
	v_mfma_i32_16x16x64_i8 v[92:95], v[194:197], v[210:213], v[92:95]
	v_mfma_i32_16x16x64_i8 v[84:87], v[186:189], v[218:221], v[84:87]
	v_mfma_i32_16x16x64_i8 v[80:83], v[194:197], v[218:221], v[80:83]
	v_mfma_i32_16x16x64_i8 v[76:79], v[186:189], v[226:229], v[76:79]
	v_mfma_i32_16x16x64_i8 v[72:75], v[194:197], v[226:229], v[72:75]
	v_mfma_i32_16x16x64_i8 v[116:119], v[190:193], v[206:209], v[116:119]
	v_mfma_i32_16x16x64_i8 v[108:111], v[198:201], v[206:209], v[108:111]
	v_mfma_i32_16x16x64_i8 v[100:103], v[190:193], v[214:217], v[100:103]
	v_mfma_i32_16x16x64_i8 v[92:95], v[198:201], v[214:217], v[92:95]
	v_mfma_i32_16x16x64_i8 v[84:87], v[190:193], v[222:225], v[84:87]
	v_mfma_i32_16x16x64_i8 v[80:83], v[198:201], v[222:225], v[80:83]
	v_mfma_i32_16x16x64_i8 v[76:79], v[190:193], v[230:233], v[76:79]
	v_mfma_i32_16x16x64_i8 v[72:75], v[198:201], v[230:233], v[72:75]
	s_barrier
	s_add_i32 s74, s57, s45
	s_mov_b32 m0, s74
	ds_read_b128 v[202:205], v180 offset:16384
	ds_read_b128 v[206:209], v180 offset:17408
	ds_read_b128 v[210:213], v180 offset:18432
	ds_read_b128 v[214:217], v180 offset:19456
	global_load_lds_dwordx4 v138, s[34:35]
	s_add_i32 m0, s74, 0x2000
	s_add_u32 s74, s34, 0x80000
	s_addc_u32 s75, s35, 0
	s_add_i32 s76, s58, s45
	global_load_lds_dwordx4 v142, s[34:35]
	s_mov_b32 m0, s76
	ds_read_b128 v[230:233], v180 offset:23552
	global_load_lds_dwordx4 v138, s[74:75]
	s_add_i32 m0, s76, 0x2000
	ds_read_b128 v[226:229], v180 offset:22528
	global_load_lds_dwordx4 v142, s[74:75]
	s_mov_b32 m0, s46
	ds_read_b128 v[222:225], v180 offset:21504
	global_load_lds_dwordx4 v136, s[36:37]
	s_mov_b32 m0, s47
	ds_read_b128 v[218:221], v180 offset:20480
	global_load_lds_dwordx4 v140, s[36:37]
	s_waitcnt vmcnt(10) lgkmcnt(0)
	s_barrier
	v_mfma_i32_16x16x64_i8 v[68:71], v[160:163], v[202:205], v[68:71]
	v_mfma_i32_16x16x64_i8 v[64:67], v[168:171], v[202:205], v[64:67]
	v_mfma_i32_16x16x64_i8 v[60:63], v[160:163], v[210:213], v[60:63]
	v_mfma_i32_16x16x64_i8 v[56:59], v[168:171], v[210:213], v[56:59]
	v_mfma_i32_16x16x64_i8 v[48:51], v[160:163], v[218:221], v[48:51]
	v_mfma_i32_16x16x64_i8 v[40:43], v[168:171], v[218:221], v[40:43]
	v_mfma_i32_16x16x64_i8 v[32:35], v[160:163], v[226:229], v[32:35]
	v_mfma_i32_16x16x64_i8 v[24:27], v[168:171], v[226:229], v[24:27]
	v_mfma_i32_16x16x64_i8 v[68:71], v[164:167], v[206:209], v[68:71]
	v_mfma_i32_16x16x64_i8 v[64:67], v[182:185], v[206:209], v[64:67]
	v_mfma_i32_16x16x64_i8 v[60:63], v[164:167], v[214:217], v[60:63]
	v_mfma_i32_16x16x64_i8 v[56:59], v[182:185], v[214:217], v[56:59]
	v_mfma_i32_16x16x64_i8 v[48:51], v[164:167], v[222:225], v[48:51]
	v_mfma_i32_16x16x64_i8 v[40:43], v[182:185], v[222:225], v[40:43]
	v_mfma_i32_16x16x64_i8 v[32:35], v[164:167], v[230:233], v[32:35]
	v_mfma_i32_16x16x64_i8 v[24:27], v[182:185], v[230:233], v[24:27]
	v_mfma_i32_16x16x64_i8 v[52:55], v[186:189], v[202:205], v[52:55]
	v_mfma_i32_16x16x64_i8 v[44:47], v[194:197], v[202:205], v[44:47]
	v_mfma_i32_16x16x64_i8 v[36:39], v[186:189], v[210:213], v[36:39]
	v_mfma_i32_16x16x64_i8 v[28:31], v[194:197], v[210:213], v[28:31]
	v_mfma_i32_16x16x64_i8 v[20:23], v[186:189], v[218:221], v[20:23]
	v_mfma_i32_16x16x64_i8 v[16:19], v[194:197], v[218:221], v[16:19]
	v_mfma_i32_16x16x64_i8 v[12:15], v[186:189], v[226:229], v[12:15]
	v_mfma_i32_16x16x64_i8 v[6:9], v[194:197], v[226:229], v[8:11]
	v_mfma_i32_16x16x64_i8 v[52:55], v[190:193], v[206:209], v[52:55]
	v_mfma_i32_16x16x64_i8 v[44:47], v[198:201], v[206:209], v[44:47]
	v_mfma_i32_16x16x64_i8 v[36:39], v[190:193], v[214:217], v[36:39]
	v_mfma_i32_16x16x64_i8 v[28:31], v[198:201], v[214:217], v[28:31]
	v_mfma_i32_16x16x64_i8 v[20:23], v[190:193], v[222:225], v[20:23]
	v_mfma_i32_16x16x64_i8 v[16:19], v[198:201], v[222:225], v[16:19]
	v_mfma_i32_16x16x64_i8 v[12:15], v[190:193], v[230:233], v[12:15]
	v_mfma_i32_16x16x64_i8 v[6:9], v[198:201], v[230:233], v[6:9]
	s_barrier
	s_add_i32 s74, 0, 0x18000
	s_add_i32 s75, 0, 0x1c000
	ds_read_b128 v[160:163], v177 offset:32768
	ds_read_b128 v[164:167], v177 offset:33792
	ds_read_b128 v[168:171], v177 offset:34816
	ds_read_b128 v[182:185], v177 offset:35840
	ds_read_b128 v[186:189], v177 offset:49152
	ds_read_b128 v[190:193], v177 offset:50176
	ds_read_b128 v[194:197], v177 offset:51200
	ds_read_b128 v[198:201], v177 offset:52224
	s_add_u32 s36, s36, 0x80000
	s_addc_u32 s37, s37, 0
	s_mov_b32 m0, s48
	ds_read_b128 v[202:205], v180 offset:32768
	ds_read_b128 v[206:209], v180 offset:33792
	ds_read_b128 v[210:213], v180 offset:34816
	ds_read_b128 v[214:217], v180 offset:35840
	ds_read_b128 v[218:221], v180 offset:36864
	ds_read_b128 v[222:225], v180 offset:37888
	ds_read_b128 v[226:229], v180 offset:38912
	global_load_lds_dwordx4 v136, s[36:37]
	s_mov_b32 m0, s49
	ds_read_b128 v[230:233], v180 offset:39936
	global_load_lds_dwordx4 v140, s[36:37]
	s_waitcnt vmcnt(8) lgkmcnt(0)
	s_barrier
	v_mfma_i32_16x16x64_i8 v[132:135], v[160:163], v[202:205], v[132:135]
	v_mfma_i32_16x16x64_i8 v[128:131], v[168:171], v[202:205], v[128:131]
	v_mfma_i32_16x16x64_i8 v[124:127], v[160:163], v[210:213], v[124:127]
	v_mfma_i32_16x16x64_i8 v[120:123], v[168:171], v[210:213], v[120:123]
	v_mfma_i32_16x16x64_i8 v[112:115], v[160:163], v[218:221], v[112:115]
	v_max3_f32 v0, v0, |v152|, |v156|
	v_mfma_i32_16x16x64_i8 v[104:107], v[168:171], v[218:221], v[104:107]
	v_max3_f32 v1, v1, |v153|, |v157|
	v_mfma_i32_16x16x64_i8 v[96:99], v[160:163], v[226:229], v[96:99]
	v_max3_f32 v2, v2, |v154|, |v158|
	v_mfma_i32_16x16x64_i8 v[88:91], v[168:171], v[226:229], v[88:91]
	v_max3_f32 v3, v3, |v155|, |v159|
	v_mfma_i32_16x16x64_i8 v[132:135], v[164:167], v[206:209], v[132:135]
	v_mfma_i32_16x16x64_i8 v[128:131], v[182:185], v[206:209], v[128:131]
	v_mfma_i32_16x16x64_i8 v[124:127], v[164:167], v[214:217], v[124:127]
	v_mfma_i32_16x16x64_i8 v[120:123], v[182:185], v[214:217], v[120:123]
	v_mfma_i32_16x16x64_i8 v[112:115], v[164:167], v[222:225], v[112:115]
	v_mfma_i32_16x16x64_i8 v[104:107], v[182:185], v[222:225], v[104:107]
	v_mfma_i32_16x16x64_i8 v[96:99], v[164:167], v[230:233], v[96:99]
	v_mfma_i32_16x16x64_i8 v[88:91], v[182:185], v[230:233], v[88:91]
	v_mfma_i32_16x16x64_i8 v[116:119], v[186:189], v[202:205], v[116:119]
	v_mfma_i32_16x16x64_i8 v[108:111], v[194:197], v[202:205], v[108:111]
	v_mfma_i32_16x16x64_i8 v[100:103], v[186:189], v[210:213], v[100:103]
	v_mfma_i32_16x16x64_i8 v[92:95], v[194:197], v[210:213], v[92:95]
	v_mfma_i32_16x16x64_i8 v[84:87], v[186:189], v[218:221], v[84:87]
	v_mfma_i32_16x16x64_i8 v[80:83], v[194:197], v[218:221], v[80:83]
	v_mfma_i32_16x16x64_i8 v[76:79], v[186:189], v[226:229], v[76:79]
	v_mfma_i32_16x16x64_i8 v[72:75], v[194:197], v[226:229], v[72:75]
	v_mfma_i32_16x16x64_i8 v[116:119], v[190:193], v[206:209], v[116:119]
	v_mfma_i32_16x16x64_i8 v[108:111], v[198:201], v[206:209], v[108:111]
	v_mfma_i32_16x16x64_i8 v[100:103], v[190:193], v[214:217], v[100:103]
	v_mfma_i32_16x16x64_i8 v[92:95], v[198:201], v[214:217], v[92:95]
	v_mfma_i32_16x16x64_i8 v[84:87], v[190:193], v[222:225], v[84:87]
	v_mfma_i32_16x16x64_i8 v[80:83], v[198:201], v[222:225], v[80:83]
	v_mfma_i32_16x16x64_i8 v[76:79], v[190:193], v[230:233], v[76:79]
	v_mfma_i32_16x16x64_i8 v[72:75], v[198:201], v[230:233], v[72:75]
	s_barrier
	s_add_u32 s98, s34, s14
	s_addc_u32 s99, s35, s15
	s_add_u32 s100, s36, s14
	s_addc_u32 s101, s37, s15
	s_sub_u32 s100, s100, 0x80000
	s_subb_u32 s101, s101, 0
	s_add_i32 s36, s74, s45
	s_mov_b32 m0, s36
	ds_read_b128 v[152:155], v180 offset:49152
	ds_read_b128 v[156:159], v180 offset:50176
	ds_read_b128 v[202:205], v180 offset:51200
	ds_read_b128 v[206:209], v180 offset:52224
	global_load_lds_dwordx4 v138, s[98:99]
	s_add_i32 m0, s36, 0x2000
	s_add_u32 s34, s34, 0x80080
	s_addc_u32 s35, s35, 0
	s_add_i32 s36, s75, s45
	global_load_lds_dwordx4 v142, s[98:99]
	s_mov_b32 m0, s36
	ds_read_b128 v[222:225], v180 offset:56320
	global_load_lds_dwordx4 v138, s[34:35]
	s_add_i32 m0, s36, 0x2000
	ds_read_b128 v[218:221], v180 offset:55296
	global_load_lds_dwordx4 v142, s[34:35]
	s_mov_b32 m0, s54
	ds_read_b128 v[214:217], v180 offset:54272
	global_load_lds_dwordx4 v136, s[100:101]
	s_mov_b32 m0, s55
	ds_read_b128 v[210:213], v180 offset:53248
	global_load_lds_dwordx4 v140, s[100:101]
	s_waitcnt vmcnt(8) lgkmcnt(0)
	s_barrier
	v_mfma_i32_16x16x64_i8 v[68:71], v[160:163], v[152:155], v[68:71]
	v_mfma_i32_16x16x64_i8 v[64:67], v[168:171], v[152:155], v[64:67]
	v_mfma_i32_16x16x64_i8 v[60:63], v[160:163], v[202:205], v[60:63]
	v_mfma_i32_16x16x64_i8 v[56:59], v[168:171], v[202:205], v[56:59]
	v_mfma_i32_16x16x64_i8 v[48:51], v[160:163], v[210:213], v[48:51]
	v_mfma_i32_16x16x64_i8 v[40:43], v[168:171], v[210:213], v[40:43]
	v_mfma_i32_16x16x64_i8 v[32:35], v[160:163], v[218:221], v[32:35]
	v_mfma_i32_16x16x64_i8 v[24:27], v[168:171], v[218:221], v[24:27]
	v_mfma_i32_16x16x64_i8 v[68:71], v[164:167], v[156:159], v[68:71]
	v_mfma_i32_16x16x64_i8 v[64:67], v[182:185], v[156:159], v[64:67]
	v_mfma_i32_16x16x64_i8 v[60:63], v[164:167], v[206:209], v[60:63]
	v_mfma_i32_16x16x64_i8 v[56:59], v[182:185], v[206:209], v[56:59]
	v_mfma_i32_16x16x64_i8 v[48:51], v[164:167], v[214:217], v[48:51]
	v_mfma_i32_16x16x64_i8 v[40:43], v[182:185], v[214:217], v[40:43]
	v_mfma_i32_16x16x64_i8 v[32:35], v[164:167], v[222:225], v[32:35]
	v_mfma_i32_16x16x64_i8 v[24:27], v[182:185], v[222:225], v[24:27]
	v_mfma_i32_16x16x64_i8 v[52:55], v[186:189], v[152:155], v[52:55]
	v_mfma_i32_16x16x64_i8 v[44:47], v[194:197], v[152:155], v[44:47]
	v_mfma_i32_16x16x64_i8 v[36:39], v[186:189], v[202:205], v[36:39]
	v_mfma_i32_16x16x64_i8 v[28:31], v[194:197], v[202:205], v[28:31]
	v_mfma_i32_16x16x64_i8 v[20:23], v[186:189], v[210:213], v[20:23]
	v_mfma_i32_16x16x64_i8 v[16:19], v[194:197], v[210:213], v[16:19]
	v_mfma_i32_16x16x64_i8 v[10:13], v[186:189], v[218:221], v[12:15]
	v_mfma_i32_16x16x64_i8 v[6:9], v[194:197], v[218:221], v[6:9]
	v_mfma_i32_16x16x64_i8 v[52:55], v[190:193], v[156:159], v[52:55]
	v_mfma_i32_16x16x64_i8 v[44:47], v[198:201], v[156:159], v[44:47]
	v_mfma_i32_16x16x64_i8 v[36:39], v[190:193], v[206:209], v[36:39]
	v_mfma_i32_16x16x64_i8 v[28:31], v[198:201], v[206:209], v[28:31]
	v_mfma_i32_16x16x64_i8 v[20:23], v[190:193], v[214:217], v[20:23]
	v_mfma_i32_16x16x64_i8 v[16:19], v[198:201], v[214:217], v[16:19]
	v_mfma_i32_16x16x64_i8 v[12:15], v[190:193], v[222:225], v[10:13]
	v_mfma_i32_16x16x64_i8 v[8:11], v[198:201], v[222:225], v[6:9]
	s_barrier
	s_add_u32 s30, s30, 0x100
	s_addc_u32 s31, s31, 0
	s_add_u32 s72, s72, 0x100
	s_addc_u32 s73, s73, 0
	s_cmp_ge_i32 s8, s66
	s_cbranch_scc0 .LBB0_312

.LBB0_1033:
	s_add_i32 s8, s71, 2
	s_add_u32 s28, s26, 0xfff00080
	s_addc_u32 s29, s27, -1
	s_cmp_eq_u32 s68, s71
	s_cselect_b32 s31, s64, s29
	s_cselect_b32 s30, s65, s28
	s_cselect_b32 s29, s66, s70
	s_cselect_b32 s28, s67, s69
	s_cmpk_lt_i32 s3, 0x56
	s_mov_b32 s76, 0xac00
	s_cselect_b32 s71, s76, 0x4000
	s_mul_i32 s72, s71, s33
	s_add_u32 s72, s34, s72
	s_addc_u32 s73, s35, 0
	global_load_dwordx4 v[152:155], v159, s[72:73] nt
	s_add_u32 s74, s72, s71
	s_addc_u32 s75, s73, 0
	global_load_dwordx4 v[168:171], v159, s[74:75] nt
	s_add_i32 s33, s33, 2
	v_add_u32_e32 v160, -2, v160
	ds_read_b128 v[172:175], v163
	ds_read_b128 v[176:179], v163 offset:1024
	ds_read_b128 v[180:183], v163 offset:2048
	ds_read_b128 v[184:187], v163 offset:3072
	ds_read_b128 v[188:191], v163 offset:16384
	ds_read_b128 v[192:195], v163 offset:17408
	ds_read_b128 v[196:199], v163 offset:18432
	ds_read_b128 v[200:203], v163 offset:19456
	s_add_i32 m0, s43, 0xc000
	ds_read_b128 v[204:207], v166
	ds_read_b128 v[208:211], v166 offset:1024
	ds_read_b128 v[212:215], v166 offset:2048
	ds_read_b128 v[216:219], v166 offset:3072
	ds_read_b128 v[220:223], v166 offset:4096
	ds_read_b128 v[224:227], v166 offset:5120
	ds_read_b128 v[236:239], v166 offset:6144
	global_load_lds_dwordx4 v146, s[26:27]
	s_add_i32 m0, s43, 0xe000
	ds_read_b128 v[240:243], v166 offset:7168
	global_load_lds_dwordx4 v148, s[26:27]
	s_waitcnt vmcnt(10) lgkmcnt(0)
	s_barrier
	v_mfma_f32_16x16x32_bf16 v[132:135], v[172:175], v[204:207], v[132:135]
	v_mfma_f32_16x16x32_bf16 v[128:131], v[180:183], v[204:207], v[128:131]
	v_mfma_f32_16x16x32_bf16 v[116:119], v[172:175], v[212:215], v[116:119]
	v_mfma_f32_16x16x32_bf16 v[112:115], v[180:183], v[212:215], v[112:115]
	v_mfma_f32_16x16x32_bf16 v[100:103], v[172:175], v[220:223], v[100:103]
	v_mfma_f32_16x16x32_bf16 v[96:99], v[180:183], v[220:223], v[96:99]
	v_mfma_f32_16x16x32_bf16 v[84:87], v[172:175], v[236:239], v[84:87]
	v_mfma_f32_16x16x32_bf16 v[80:83], v[180:183], v[236:239], v[80:83]
	v_mfma_f32_16x16x32_bf16 v[132:135], v[176:179], v[208:211], v[132:135]
	v_mfma_f32_16x16x32_bf16 v[128:131], v[184:187], v[208:211], v[128:131]
	v_mfma_f32_16x16x32_bf16 v[116:119], v[176:179], v[216:219], v[116:119]
	v_mfma_f32_16x16x32_bf16 v[112:115], v[184:187], v[216:219], v[112:115]
	v_mfma_f32_16x16x32_bf16 v[100:103], v[176:179], v[224:227], v[100:103]
	v_mfma_f32_16x16x32_bf16 v[96:99], v[184:187], v[224:227], v[96:99]
	v_mfma_f32_16x16x32_bf16 v[84:87], v[176:179], v[240:243], v[84:87]
	v_mfma_f32_16x16x32_bf16 v[80:83], v[184:187], v[240:243], v[80:83]
	v_mfma_f32_16x16x32_bf16 v[124:127], v[188:191], v[204:207], v[124:127]
	v_mfma_f32_16x16x32_bf16 v[120:123], v[196:199], v[204:207], v[120:123]
	v_mfma_f32_16x16x32_bf16 v[108:111], v[188:191], v[212:215], v[108:111]
	v_mfma_f32_16x16x32_bf16 v[104:107], v[196:199], v[212:215], v[104:107]
	v_mfma_f32_16x16x32_bf16 v[92:95], v[188:191], v[220:223], v[92:95]
	v_mfma_f32_16x16x32_bf16 v[88:91], v[196:199], v[220:223], v[88:91]
	v_mfma_f32_16x16x32_bf16 v[76:79], v[188:191], v[236:239], v[76:79]
	v_mfma_f32_16x16x32_bf16 v[72:75], v[196:199], v[236:239], v[72:75]
	v_mfma_f32_16x16x32_bf16 v[124:127], v[192:195], v[208:211], v[124:127]
	v_mfma_f32_16x16x32_bf16 v[120:123], v[200:203], v[208:211], v[120:123]
	v_mfma_f32_16x16x32_bf16 v[108:111], v[192:195], v[216:219], v[108:111]
	v_mfma_f32_16x16x32_bf16 v[104:107], v[200:203], v[216:219], v[104:107]
	v_mfma_f32_16x16x32_bf16 v[92:95], v[192:195], v[224:227], v[92:95]
	v_mfma_f32_16x16x32_bf16 v[88:91], v[200:203], v[224:227], v[88:91]
	v_mfma_f32_16x16x32_bf16 v[76:79], v[192:195], v[240:243], v[76:79]
	v_mfma_f32_16x16x32_bf16 v[72:75], v[200:203], v[240:243], v[72:75]
	s_barrier
	s_add_i32 s71, s53, s40
	s_mov_b32 m0, s71
	ds_read_b128 v[204:207], v166 offset:16384
	ds_read_b128 v[208:211], v166 offset:17408
	ds_read_b128 v[212:215], v166 offset:18432
	ds_read_b128 v[216:219], v166 offset:19456
	global_load_lds_dwordx4 v138, s[28:29]
	s_add_i32 m0, s71, 0x2000
	s_add_u32 s72, s28, 0x100000
	s_addc_u32 s73, s29, 0
	s_add_i32 s71, s54, s40
	global_load_lds_dwordx4 v142, s[28:29]
	s_mov_b32 m0, s71
	ds_read_b128 v[240:243], v166 offset:23552
	global_load_lds_dwordx4 v138, s[72:73]
	s_add_i32 m0, s71, 0x2000
	ds_read_b128 v[236:239], v166 offset:22528
	global_load_lds_dwordx4 v142, s[72:73]
	s_mov_b32 m0, s43
	ds_read_b128 v[224:227], v166 offset:21504
	global_load_lds_dwordx4 v136, s[30:31]
	s_mov_b32 m0, s44
	ds_read_b128 v[220:223], v166 offset:20480
	global_load_lds_dwordx4 v140, s[30:31]
	s_waitcnt vmcnt(10) lgkmcnt(0)
	s_barrier
	v_mfma_f32_16x16x32_bf16 v[68:71], v[172:175], v[204:207], v[68:71]
	v_mfma_f32_16x16x32_bf16 v[64:67], v[180:183], v[204:207], v[64:67]
	v_mfma_f32_16x16x32_bf16 v[52:55], v[172:175], v[212:215], v[52:55]
	v_mfma_f32_16x16x32_bf16 v[48:51], v[180:183], v[212:215], v[48:51]
	v_mfma_f32_16x16x32_bf16 v[36:39], v[172:175], v[220:223], v[36:39]
	v_mfma_f32_16x16x32_bf16 v[32:35], v[180:183], v[220:223], v[32:35]
	v_mfma_f32_16x16x32_bf16 v[20:23], v[172:175], v[236:239], v[20:23]
	v_mfma_f32_16x16x32_bf16 v[16:19], v[180:183], v[236:239], v[16:19]
	v_mfma_f32_16x16x32_bf16 v[68:71], v[176:179], v[208:211], v[68:71]
	v_mfma_f32_16x16x32_bf16 v[64:67], v[184:187], v[208:211], v[64:67]
	v_mfma_f32_16x16x32_bf16 v[52:55], v[176:179], v[216:219], v[52:55]
	v_mfma_f32_16x16x32_bf16 v[48:51], v[184:187], v[216:219], v[48:51]
	v_mfma_f32_16x16x32_bf16 v[36:39], v[176:179], v[224:227], v[36:39]
	v_mfma_f32_16x16x32_bf16 v[32:35], v[184:187], v[224:227], v[32:35]
	v_mfma_f32_16x16x32_bf16 v[20:23], v[176:179], v[240:243], v[20:23]
	v_mfma_f32_16x16x32_bf16 v[16:19], v[184:187], v[240:243], v[16:19]
	v_mfma_f32_16x16x32_bf16 v[60:63], v[188:191], v[204:207], v[60:63]
	v_mfma_f32_16x16x32_bf16 v[56:59], v[196:199], v[204:207], v[56:59]
	v_mfma_f32_16x16x32_bf16 v[44:47], v[188:191], v[212:215], v[44:47]
	v_mfma_f32_16x16x32_bf16 v[40:43], v[196:199], v[212:215], v[40:43]
	v_mfma_f32_16x16x32_bf16 v[28:31], v[188:191], v[220:223], v[28:31]
	v_mfma_f32_16x16x32_bf16 v[24:27], v[196:199], v[220:223], v[24:27]
	v_mfma_f32_16x16x32_bf16 v[12:15], v[188:191], v[236:239], v[12:15]
	v_mfma_f32_16x16x32_bf16 v[6:9], v[196:199], v[236:239], v[8:11]
	v_mfma_f32_16x16x32_bf16 v[60:63], v[192:195], v[208:211], v[60:63]
	v_mfma_f32_16x16x32_bf16 v[56:59], v[200:203], v[208:211], v[56:59]
	v_mfma_f32_16x16x32_bf16 v[44:47], v[192:195], v[216:219], v[44:47]
	v_mfma_f32_16x16x32_bf16 v[40:43], v[200:203], v[216:219], v[40:43]
	v_mfma_f32_16x16x32_bf16 v[28:31], v[192:195], v[224:227], v[28:31]
	v_mfma_f32_16x16x32_bf16 v[24:27], v[200:203], v[224:227], v[24:27]
	v_mfma_f32_16x16x32_bf16 v[12:15], v[192:195], v[240:243], v[12:15]
	v_mfma_f32_16x16x32_bf16 v[6:9], v[200:203], v[240:243], v[6:9]
	s_barrier
	s_add_i32 s71, 0, 0x18000
	s_add_i32 s72, 0, 0x1c000
	ds_read_b128 v[172:175], v163 offset:32768
	ds_read_b128 v[176:179], v163 offset:33792
	ds_read_b128 v[180:183], v163 offset:34816
	ds_read_b128 v[184:187], v163 offset:35840
	ds_read_b128 v[188:191], v163 offset:49152
	ds_read_b128 v[192:195], v163 offset:50176
	ds_read_b128 v[196:199], v163 offset:51200
	ds_read_b128 v[200:203], v163 offset:52224
	s_add_u32 s30, s30, 0x100000
	s_addc_u32 s31, s31, 0
	s_mov_b32 m0, s45
	ds_read_b128 v[204:207], v166 offset:32768
	ds_read_b128 v[208:211], v166 offset:33792
	ds_read_b128 v[212:215], v166 offset:34816
	ds_read_b128 v[216:219], v166 offset:35840
	ds_read_b128 v[220:223], v166 offset:36864
	ds_read_b128 v[224:227], v166 offset:37888
	ds_read_b128 v[236:239], v166 offset:38912
	global_load_lds_dwordx4 v136, s[30:31]
	s_mov_b32 m0, s46
	ds_read_b128 v[240:243], v166 offset:39936
	global_load_lds_dwordx4 v140, s[30:31]
	s_waitcnt vmcnt(8) lgkmcnt(0)
	s_barrier
	v_mfma_f32_16x16x32_bf16 v[132:135], v[172:175], v[204:207], v[132:135]
	v_mfma_f32_16x16x32_bf16 v[128:131], v[180:183], v[204:207], v[128:131]
	v_mfma_f32_16x16x32_bf16 v[116:119], v[172:175], v[212:215], v[116:119]
	v_mfma_f32_16x16x32_bf16 v[112:115], v[180:183], v[212:215], v[112:115]
	v_mfma_f32_16x16x32_bf16 v[100:103], v[172:175], v[220:223], v[100:103]
	v_max3_f32 v0, v0, |v152|, |v168|
	v_mfma_f32_16x16x32_bf16 v[96:99], v[180:183], v[220:223], v[96:99]
	v_max3_f32 v1, v1, |v153|, |v169|
	v_mfma_f32_16x16x32_bf16 v[84:87], v[172:175], v[236:239], v[84:87]
	v_max3_f32 v2, v2, |v154|, |v170|
	v_mfma_f32_16x16x32_bf16 v[80:83], v[180:183], v[236:239], v[80:83]
	v_max3_f32 v3, v3, |v155|, |v171|
	v_mfma_f32_16x16x32_bf16 v[132:135], v[176:179], v[208:211], v[132:135]
	v_mfma_f32_16x16x32_bf16 v[128:131], v[184:187], v[208:211], v[128:131]
	v_mfma_f32_16x16x32_bf16 v[116:119], v[176:179], v[216:219], v[116:119]
	v_mfma_f32_16x16x32_bf16 v[112:115], v[184:187], v[216:219], v[112:115]
	v_mfma_f32_16x16x32_bf16 v[100:103], v[176:179], v[224:227], v[100:103]
	v_mfma_f32_16x16x32_bf16 v[96:99], v[184:187], v[224:227], v[96:99]
	v_mfma_f32_16x16x32_bf16 v[84:87], v[176:179], v[240:243], v[84:87]
	v_mfma_f32_16x16x32_bf16 v[80:83], v[184:187], v[240:243], v[80:83]
	v_mfma_f32_16x16x32_bf16 v[124:127], v[188:191], v[204:207], v[124:127]
	v_mfma_f32_16x16x32_bf16 v[120:123], v[196:199], v[204:207], v[120:123]
	v_mfma_f32_16x16x32_bf16 v[108:111], v[188:191], v[212:215], v[108:111]
	v_mfma_f32_16x16x32_bf16 v[104:107], v[196:199], v[212:215], v[104:107]
	v_mfma_f32_16x16x32_bf16 v[92:95], v[188:191], v[220:223], v[92:95]
	v_mfma_f32_16x16x32_bf16 v[88:91], v[196:199], v[220:223], v[88:91]
	v_mfma_f32_16x16x32_bf16 v[76:79], v[188:191], v[236:239], v[76:79]
	v_mfma_f32_16x16x32_bf16 v[72:75], v[196:199], v[236:239], v[72:75]
	v_mfma_f32_16x16x32_bf16 v[124:127], v[192:195], v[208:211], v[124:127]
	v_mfma_f32_16x16x32_bf16 v[120:123], v[200:203], v[208:211], v[120:123]
	v_mfma_f32_16x16x32_bf16 v[108:111], v[192:195], v[216:219], v[108:111]
	v_mfma_f32_16x16x32_bf16 v[104:107], v[200:203], v[216:219], v[104:107]
	v_mfma_f32_16x16x32_bf16 v[92:95], v[192:195], v[224:227], v[92:95]
	v_mfma_f32_16x16x32_bf16 v[88:91], v[200:203], v[224:227], v[88:91]
	v_mfma_f32_16x16x32_bf16 v[76:79], v[192:195], v[240:243], v[76:79]
	v_mfma_f32_16x16x32_bf16 v[72:75], v[200:203], v[240:243], v[72:75]
	s_barrier
	s_add_u32 s74, s28, s6
	s_addc_u32 s75, s29, s7
	s_add_u32 s76, s30, s6
	s_addc_u32 s77, s31, s7
	s_sub_u32 s76, s76, 0x100000
	s_subb_u32 s77, s77, 0
	s_add_i32 s30, s71, s40
	s_mov_b32 m0, s30
	ds_read_b128 v[152:155], v166 offset:49152
	ds_read_b128 v[168:171], v166 offset:50176
	ds_read_b128 v[204:207], v166 offset:51200
	ds_read_b128 v[208:211], v166 offset:52224
	global_load_lds_dwordx4 v138, s[74:75]
	s_add_i32 m0, s30, 0x2000
	s_add_u32 s28, s28, 0x100080
	s_addc_u32 s29, s29, 0
	s_add_i32 s30, s72, s40
	global_load_lds_dwordx4 v142, s[74:75]
	s_mov_b32 m0, s30
	ds_read_b128 v[224:227], v166 offset:56320
	global_load_lds_dwordx4 v138, s[28:29]
	s_add_i32 m0, s30, 0x2000
	ds_read_b128 v[220:223], v166 offset:55296
	global_load_lds_dwordx4 v142, s[28:29]
	s_mov_b32 m0, s49
	ds_read_b128 v[216:219], v166 offset:54272
	global_load_lds_dwordx4 v136, s[76:77]
	s_mov_b32 m0, s50
	ds_read_b128 v[212:215], v166 offset:53248
	global_load_lds_dwordx4 v140, s[76:77]
	s_waitcnt vmcnt(8) lgkmcnt(0)
	s_barrier
	v_mfma_f32_16x16x32_bf16 v[68:71], v[172:175], v[152:155], v[68:71]
	v_mfma_f32_16x16x32_bf16 v[64:67], v[180:183], v[152:155], v[64:67]
	v_mfma_f32_16x16x32_bf16 v[52:55], v[172:175], v[204:207], v[52:55]
	v_mfma_f32_16x16x32_bf16 v[48:51], v[180:183], v[204:207], v[48:51]
	v_mfma_f32_16x16x32_bf16 v[36:39], v[172:175], v[212:215], v[36:39]
	v_mfma_f32_16x16x32_bf16 v[32:35], v[180:183], v[212:215], v[32:35]
	v_mfma_f32_16x16x32_bf16 v[20:23], v[172:175], v[220:223], v[20:23]
	v_mfma_f32_16x16x32_bf16 v[16:19], v[180:183], v[220:223], v[16:19]
	v_mfma_f32_16x16x32_bf16 v[68:71], v[176:179], v[168:171], v[68:71]
	v_mfma_f32_16x16x32_bf16 v[64:67], v[184:187], v[168:171], v[64:67]
	v_mfma_f32_16x16x32_bf16 v[52:55], v[176:179], v[208:211], v[52:55]
	v_mfma_f32_16x16x32_bf16 v[48:51], v[184:187], v[208:211], v[48:51]
	v_mfma_f32_16x16x32_bf16 v[36:39], v[176:179], v[216:219], v[36:39]
	v_mfma_f32_16x16x32_bf16 v[32:35], v[184:187], v[216:219], v[32:35]
	v_mfma_f32_16x16x32_bf16 v[20:23], v[176:179], v[224:227], v[20:23]
	v_mfma_f32_16x16x32_bf16 v[16:19], v[184:187], v[224:227], v[16:19]
	v_mfma_f32_16x16x32_bf16 v[60:63], v[188:191], v[152:155], v[60:63]
	v_mfma_f32_16x16x32_bf16 v[56:59], v[196:199], v[152:155], v[56:59]
	v_mfma_f32_16x16x32_bf16 v[44:47], v[188:191], v[204:207], v[44:47]
	v_mfma_f32_16x16x32_bf16 v[40:43], v[196:199], v[204:207], v[40:43]
	v_mfma_f32_16x16x32_bf16 v[28:31], v[188:191], v[212:215], v[28:31]
	v_mfma_f32_16x16x32_bf16 v[24:27], v[196:199], v[212:215], v[24:27]
	v_mfma_f32_16x16x32_bf16 v[10:13], v[188:191], v[220:223], v[12:15]
	v_mfma_f32_16x16x32_bf16 v[6:9], v[196:199], v[220:223], v[6:9]
	v_mfma_f32_16x16x32_bf16 v[60:63], v[192:195], v[168:171], v[60:63]
	v_mfma_f32_16x16x32_bf16 v[56:59], v[200:203], v[168:171], v[56:59]
	v_mfma_f32_16x16x32_bf16 v[44:47], v[192:195], v[208:211], v[44:47]
	v_mfma_f32_16x16x32_bf16 v[40:43], v[200:203], v[208:211], v[40:43]
	v_mfma_f32_16x16x32_bf16 v[28:31], v[192:195], v[216:219], v[28:31]
	v_mfma_f32_16x16x32_bf16 v[24:27], v[200:203], v[216:219], v[24:27]
	v_mfma_f32_16x16x32_bf16 v[12:15], v[192:195], v[224:227], v[10:13]
	v_mfma_f32_16x16x32_bf16 v[8:11], v[200:203], v[224:227], v[6:9]
	s_barrier
	s_add_u32 s26, s26, 0x100
	s_addc_u32 s27, s27, 0
	s_add_u32 s69, s69, 0x100
	s_addc_u32 s70, s70, 0
	s_cmp_ge_i32 s8, s63
	s_cbranch_scc0 .LBB0_1018
